# D4 score loop: 1-state pads left by the removed canonicalising max dropped wherever ISA Table 38 MFMA->VALU distances still hold
# baseline (speedup 1.0000x reference)
; __device__ __forceinline__ void dsa_index_phase(const Params& p, unsigned char* smem) {
;     ...
;                 f32x4 sc = {0.f, 0.f, 0.f, 0.f}, sd = {0.f, 0.f, 0.f, 0.f};
; #pragma unroll
;                 for (int h = 0; h < 8; ++h) {
;                     f32x4 acc = {0.f, 0.f, 0.f, 0.f}, acd = {0.f, 0.f, 0.f, 0.f};
;                     acc = __builtin_amdgcn_mfma_f32_16x16x32_f16(k0, qf[h][0], acc, 0, 0, 0);
;                     acd = __builtin_amdgcn_mfma_f32_16x16x32_f16(k2, qf[h][0], acd, 0, 0, 0);
;                     acc = __builtin_amdgcn_mfma_f32_16x16x32_f16(k1, qf[h][1], acc, 0, 0, 0);
;                     acd = __builtin_amdgcn_mfma_f32_16x16x32_f16(k3, qf[h][1], acd, 0, 0, 0);
; #pragma unroll
;                     for (int jj = 0; jj < 4; ++jj) { sc[jj] += fmaxf(acc[jj], 0.f) * wq[h]; sd[jj] += fmaxf(acd[jj], 0.f) * wq[h]; }
;                 }
;                 *(f32x4*)(SC + r * ROWP + s0 + q * 4) = sc;
;                 if (two) *(f32x4*)(SC + r * ROWP + s1 + q * 4) = sd;
.LBB0_119:
	s_or_b64 exec, exec, s[8:9]
	v_mfma_f32_16x16x32_f16 v[16:19], v[116:119], v[32:35], 0
	v_cmp_ge_i32_e64 s[0:1], s12, v20
	v_mfma_f32_16x16x32_f16 v[26:29], v[112:115], v[36:39], v[16:19]
	v_mfma_f32_16x16x32_f16 v[22:25], v[108:111], v[32:35], 0
	v_mfma_f32_16x16x32_f16 v[16:19], v[104:107], v[36:39], v[22:25]
	s_nop 5
	v_max_f32_e32 v208, 0, v26
	v_max_f32_e32 v209, 0, v27
	v_max_f32_e32 v210, 0, v28
	v_max_f32_e32 v20, v29, v29
	v_mfma_f32_16x16x32_f16 v[28:31], v[116:119], v[56:59], 0
	v_max_f32_e32 v211, 0, v20
	v_pk_fma_f32 v[210:211], v[132:133], v[210:211], 0 op_sel_hi:[1,1,0]
	v_mfma_f32_16x16x32_f16 v[22:25], v[116:119], v[40:43], 0
	v_mfma_f32_16x16x32_f16 v[120:123], v[108:111], v[40:43], 0
	v_mfma_f32_16x16x32_f16 v[28:31], v[112:115], v[60:63], v[28:31]
	v_mfma_f32_16x16x32_f16 v[24:27], v[112:115], v[44:47], v[22:25]
	v_mfma_f32_16x16x32_f16 v[20:23], v[104:107], v[44:47], v[120:123]
	s_nop 5
	v_max_f32_e32 v216, 0, v28
	v_mfma_f32_16x16x32_f16 v[120:123], v[116:119], v[64:67], 0
	v_max_f32_e32 v217, 0, v29
	v_max_f32_e32 v218, 0, v30
	v_max_f32_e32 v195, v31, v31
	v_mfma_f32_16x16x32_f16 v[28:31], v[112:115], v[68:71], v[120:123]
	v_max_f32_e32 v219, 0, v195
	s_nop 0
	v_max_f32_e32 v212, 0, v24
	v_mfma_f32_16x16x32_f16 v[120:123], v[116:119], v[72:75], 0
	s_nop 0
	s_nop 2
	v_max_f32_e32 v220, 0, v28
	v_max_f32_e32 v221, 0, v29
	v_max_f32_e32 v222, 0, v30
	v_max_f32_e32 v223, 0, v31
	v_mfma_f32_16x16x32_f16 v[28:31], v[112:115], v[76:79], v[120:123]
	v_max_f32_e32 v213, 0, v25
	s_nop 0
	v_max_f32_e32 v214, 0, v26
	v_mfma_f32_16x16x32_f16 v[120:123], v[116:119], v[80:83], 0
	s_nop 0
	s_nop 2
	v_max_f32_e32 v224, 0, v28
	v_mfma_f32_16x16x32_f16 v[120:123], v[112:115], v[84:87], v[120:123]
	s_nop 0
	v_max_f32_e32 v225, 0, v29
	s_nop 0
	v_mfma_f32_16x16x32_f16 v[204:207], v[116:119], v[88:91], 0
	v_max_f32_e32 v238, 0, v30
	s_nop 2
	v_max_f32_e32 v240, 0, v120
	v_max_f32_e32 v241, 0, v121
	v_max_f32_e32 v246, 0, v122
	v_max_f32_e32 v195, v123, v123
	v_mfma_f32_16x16x32_f16 v[120:123], v[112:115], v[92:95], v[204:207]
	s_nop 0
	v_max_f32_e32 v215, 0, v27
	v_max_f32_e32 v239, 0, v31
	v_mfma_f32_16x16x32_f16 v[116:119], v[116:119], v[96:99], 0
	v_max_f32_e32 v247, 0, v195
	s_nop 2
	v_max_f32_e32 v204, 0, v120
	v_max_f32_e32 v205, 0, v121
	v_max_f32_e32 v206, 0, v122
	v_max_f32_e32 v207, 0, v123
	v_mfma_f32_16x16x32_f16 v[118:121], v[112:115], v[100:103], v[116:119]
	v_fma_f32 v210, v134, v214, v210
	v_fma_f32 v211, v135, v215, v211
	v_pk_fma_f32 v[210:211], v[136:137], v[218:219], v[210:211]
	v_mfma_f32_16x16x32_f16 v[24:27], v[108:111], v[56:59], 0
	v_fma_f32 v210, v138, v222, v210
	v_fma_f32 v211, v139, v223, v211
	s_nop 1
	v_max_f32_e32 v123, 0, v119
	v_pk_fma_f32 v[116:117], v[132:133], v[208:209], 0 op_sel_hi:[1,1,0]
	v_pk_fma_f32 v[116:117], v[134:135], v[212:213], v[116:117]
	v_max_f32_e32 v122, 0, v118
	v_pk_fma_f32 v[116:117], v[136:137], v[216:217], v[116:117]
	v_pk_fma_f32 v[116:117], v[138:139], v[220:221], v[116:117]
	v_mfma_f32_16x16x32_f16 v[28:31], v[108:111], v[64:67], 0
	v_fma_f32 v208, v140, v224, v116
	v_fma_f32 v209, v141, v225, v117
	v_max_f32_e32 v195, v121, v121
	v_pk_fma_f32 v[208:209], v[142:143], v[240:241], v[208:209]
	v_mfma_f32_16x16x32_f16 v[112:115], v[108:111], v[72:75], 0
	v_fma_f32 v204, v144, v204, v208
	v_fma_f32 v205, v145, v205, v209
	v_max_f32_e32 v208, 0, v120
	v_pk_fma_f32 v[204:205], v[146:147], v[122:123], v[204:205]
	v_mfma_f32_16x16x32_f16 v[116:119], v[108:111], v[80:83], 0
	v_fma_f32 v210, v140, v238, v210
	v_fma_f32 v211, v141, v239, v211
	v_max_f32_e32 v209, 0, v195
	v_pk_fma_f32 v[210:211], v[142:143], v[246:247], v[210:211]
	v_mfma_f32_16x16x32_f16 v[120:123], v[108:111], v[88:91], 0
	v_fma_f32 v206, v144, v206, v210
	v_fma_f32 v207, v145, v207, v211
	v_pk_fma_f32 v[206:207], v[146:147], v[208:209], v[206:207]
	v_mfma_f32_16x16x32_f16 v[108:111], v[108:111], v[96:99], 0
	ds_write_b128 v193, v[204:207]
	v_mfma_f32_16x16x32_f16 v[24:27], v[104:107], v[60:63], v[24:27]
	v_mfma_f32_16x16x32_f16 v[28:31], v[104:107], v[68:71], v[28:31]
	v_mfma_f32_16x16x32_f16 v[112:115], v[104:107], v[76:79], v[112:115]
	v_mfma_f32_16x16x32_f16 v[116:119], v[104:107], v[84:87], v[116:119]
	v_mfma_f32_16x16x32_f16 v[120:123], v[104:107], v[92:95], v[120:123]
	v_mfma_f32_16x16x32_f16 v[104:107], v[104:107], v[100:103], v[108:111]
	s_and_saveexec_b64 s[8:9], s[0:1]
	s_cbranch_execz .LBB0_116
	s_nop 2
	v_max_f32_e32 v109, 0, v115
	v_max_f32_e32 v111, 0, v119
	v_max_f32_e32 v115, 0, v123
	v_max_f32_e32 v16, 0, v16
	v_max_f32_e32 v17, 0, v17
	v_max_f32_e32 v20, 0, v20
	v_max_f32_e32 v112, 0, v112
	v_max_f32_e32 v21, 0, v21
	v_pk_fma_f32 v[16:17], v[132:133], v[16:17], 0 op_sel_hi:[1,1,0]
	v_max_f32_e32 v19, 0, v19
	v_max_f32_e32 v116, 0, v116
	v_pk_fma_f32 v[16:17], v[134:135], v[20:21], v[16:17]
	v_max_f32_e32 v18, 0, v18
	v_max_f32_e32 v23, 0, v23
	v_max_f32_e32 v120, 0, v120
	v_max_f32_e32 v22, 0, v22
	v_pk_fma_f32 v[18:19], v[132:133], v[18:19], 0 op_sel_hi:[1,1,0]
	v_max_f32_e32 v27, 0, v27
	v_max_f32_e32 v24, 0, v24
	v_max_f32_e32 v25, 0, v25
	v_max_f32_e32 v113, 0, v113
	v_max_f32_e32 v26, 0, v26
	v_pk_fma_f32 v[18:19], v[134:135], v[22:23], v[18:19]
	v_max_f32_e32 v31, 0, v31
	v_max_f32_e32 v28, 0, v28
	v_max_f32_e32 v29, 0, v29
	v_max_f32_e32 v117, 0, v117
	v_pk_fma_f32 v[16:17], v[136:137], v[24:25], v[16:17]
	v_max_f32_e32 v30, 0, v30
	v_pk_fma_f32 v[18:19], v[136:137], v[26:27], v[18:19]
	v_max_f32_e32 v121, 0, v121
	v_pk_fma_f32 v[16:17], v[138:139], v[28:29], v[16:17]
	v_max_f32_e32 v108, 0, v114
	v_pk_fma_f32 v[18:19], v[138:139], v[30:31], v[18:19]
	v_pk_fma_f32 v[16:17], v[140:141], v[112:113], v[16:17]
	v_max_f32_e32 v110, 0, v118
	v_pk_fma_f32 v[18:19], v[140:141], v[108:109], v[18:19]
	v_pk_fma_f32 v[16:17], v[142:143], v[116:117], v[16:17]
	v_max_f32_e32 v114, 0, v122
	v_max_f32_e32 v20, v106, v106
	v_pk_fma_f32 v[18:19], v[142:143], v[110:111], v[18:19]
	v_max_f32_e32 v107, 0, v107
	v_max_f32_e32 v104, 0, v104
	v_max_f32_e32 v105, 0, v105
	v_pk_fma_f32 v[16:17], v[144:145], v[120:121], v[16:17]
	v_max_f32_e32 v106, 0, v20
	v_pk_fma_f32 v[18:19], v[144:145], v[114:115], v[18:19]
	v_pk_fma_f32 v[16:17], v[146:147], v[104:105], v[16:17]
	v_pk_fma_f32 v[18:19], v[146:147], v[106:107], v[18:19]
	ds_write_b128 v193, v[16:19] offset:512
	s_branch .LBB0_116
